# v26 + attention kv loops: rare blocks (reference refresh, late-max subtract, rescale, pending subtract) moved out of line, tests inverted so the common path falls through instead of taking 3-4 skip br
# baseline (speedup 1.0000x reference)
.LBB0_733:
	s_add_i32 s16, s16, 2
	v_cmp_neq_f32_e64 s[0:1], -v220, v191
	s_cmp_eq_u64 s[0:1], 0
	v_sub_f32_e32 v192, 0, v220
	s_cselect_b64 s[48:49], -1, 0
	v_mov_b32_e32 v190, 0
	s_cmp_lg_u64 s[48:49], 0
	s_cbranch_scc0 .Lcold_0
.Lnegc_keep_0:
	s_min_u32 s4, s16, 29
	s_add_i32 s6, s4, 2
	v_mad_u64_u32 v[66:67], s[0:1], v194, s6, v[206:207]
	global_load_dwordx4 v[162:165], v[66:67], off
	v_mad_u64_u32 v[66:67], s[0:1], v208, s6, v[210:211]
	global_load_dwordx4 v[158:161], v[66:67], off
	global_load_dwordx4 v[154:157], v[214:215], off
	ds_read_b128 v[66:69], v219 offset:13312
	ds_read_b128 v[174:177], v219 offset:13344
	ds_read_b128 v[86:89], v219 offset:19968
	ds_read_b128 v[186:189], v219 offset:13376
	ds_read_b128 v[178:181], v219 offset:20000
	ds_read_b128 v[182:185], v219 offset:20032
	v_max3_f32 v0, v240, v50, v51
	v_max3_f32 v70, v240, v52, v53
	s_nop 0
	v_max3_f32 v0, v0, v34, v35
	v_max3_f32 v70, v70, v36, v37
	s_waitcnt lgkmcnt(5)
	v_mfma_f32_32x32x16_bf16 v[98:113], v[66:69], v[130:133], v[114:129]
	ds_read_b128 v[94:97], v219 offset:13408
	ds_read_b128 v[82:85], v219 offset:20064
	v_max3_f32 v0, v0, v54, v55
	v_max3_f32 v70, v70, v56, v57
	s_nop 0
	v_max3_f32 v0, v0, v38, v39
	v_max3_f32 v70, v70, v40, v41
	s_nop 0
	v_max3_f32 v66, v70, v60, v61
	v_max3_f32 v0, v0, v58, v59
	s_nop 0
	v_max3_f32 v193, v66, v44, v45
	s_waitcnt lgkmcnt(5)
	v_mfma_f32_32x32x16_bf16 v[66:81], v[86:89], v[130:133], v[114:129]
	v_max3_f32 v0, v0, v42, v43
	ds_read_b128 v[90:93], v219 offset:13440
	ds_read_b128 v[86:89], v219 offset:20096
	ds_read_b64_tr_b16 v[170:171], v221 offset:26624
	ds_read_b64_tr_b16 v[172:173], v221 offset:27136
	ds_read_b64_tr_b16 v[166:167], v221 offset:30720
	ds_read_b64_tr_b16 v[168:169], v221 offset:31232
	v_mfma_f32_32x32x16_bf16 v[98:113], v[174:177], v[134:137], v[98:113]
	v_max3_f32 v0, v0, v62, v63
	v_max3_f32 v174, v193, v64, v65
	s_nop 0
	v_max3_f32 v0, v0, v46, v47
	v_max3_f32 v174, v174, v48, v49
	s_waitcnt lgkmcnt(9)
	v_mfma_f32_32x32x16_bf16 v[66:81], v[178:181], v[134:137], v[66:81]
	v_max_f32_e32 v0, v0, v174
	s_nop 0
	v_mov_b32_e32 v174, v0
	s_nop 1
	v_permlane32_swap_b32_e32 v0, v174
	v_max_f32_e32 v0, v0, v174
	s_nop 0
	v_cmp_lt_f32_e32 vcc, s2, v0
	v_cmp_gt_f32_e64 s[0:1], s3, v0
	s_or_b64 vcc, vcc, s[0:1]
	s_cmp_lg_u64 vcc, 0
	s_cselect_b64 s[14:15], -1, 0
	s_cbranch_vccnz .Lcold_1

.LBB0_736:
	ds_read_b128 v[224:227], v219 offset:13472
	ds_read_b128 v[228:231], v219 offset:20128
	ds_read_b64_tr_b16 v[178:179], v221 offset:27648
	ds_read_b64_tr_b16 v[180:181], v221 offset:28160
	ds_read_b64_tr_b16 v[174:175], v221 offset:31744
	ds_read_b64_tr_b16 v[176:177], v221 offset:32256
	v_mfma_f32_32x32x16_bf16 v[98:113], v[186:189], v[138:141], v[98:113]
	v_exp_f32_e32 v50, v50
	v_exp_f32_e32 v51, v51
	v_exp_f32_e32 v52, v52
	v_exp_f32_e32 v53, v53
	s_waitcnt lgkmcnt(14)
	v_mfma_f32_32x32x16_bf16 v[66:81], v[182:185], v[138:141], v[66:81]
	v_exp_f32_e32 v54, v54
	v_exp_f32_e32 v182, v55
	v_exp_f32_e32 v56, v56
	v_exp_f32_e32 v183, v57
	s_waitcnt lgkmcnt(13)
	v_mfma_f32_32x32x16_bf16 v[98:113], v[94:97], v[142:145], v[98:113]
	v_exp_f32_e32 v55, v58
	v_exp_f32_e32 v57, v59
	v_exp_f32_e32 v58, v60
	v_exp_f32_e32 v59, v61
	s_waitcnt lgkmcnt(12)
	v_mfma_f32_32x32x16_bf16 v[66:81], v[82:85], v[142:145], v[66:81]
	v_exp_f32_e32 v60, v62
	v_exp_f32_e32 v61, v63
	v_exp_f32_e32 v62, v64
	v_exp_f32_e32 v63, v65
	s_waitcnt lgkmcnt(11)
	v_mfma_f32_32x32x16_bf16 v[98:113], v[90:93], v[146:149], v[98:113]
	s_waitcnt lgkmcnt(10)
	v_mfma_f32_32x32x16_bf16 v[66:81], v[86:89], v[146:149], v[66:81]
	s_waitcnt lgkmcnt(5)
	v_mfma_f32_32x32x16_bf16 v[98:113], v[224:227], v[150:153], v[98:113]
	s_waitcnt lgkmcnt(4)
	v_mfma_f32_32x32x16_bf16 v[66:81], v[228:231], v[150:153], v[66:81]
	v_cmp_eq_f32_e32 vcc, 1.0, v0
	s_cmp_lg_u64 vcc, exec
	s_cbranch_scc1 .Lcold_2

.LBB0_742:
	s_or_b64 exec, exec, s[0:1]
	s_waitcnt lgkmcnt(5)
	v_mfma_f32_32x32x16_bf16 v[18:33], v[34:37], v[38:41], v[18:33]
	v_mfma_f32_32x32x16_bf16 v[82:97], v[198:201], v[46:49], v[82:97]
	s_waitcnt vmcnt(0)
	ds_write_b128 v217, v[154:157] offset:34816
	s_waitcnt lgkmcnt(4)
	v_mfma_f32_32x32x16_bf16 v[2:17], v[50:53], v[46:49], v[2:17]
	s_waitcnt lgkmcnt(2)
	v_mfma_f32_32x32x16_bf16 v[18:33], v[42:45], v[46:49], v[18:33]
	s_and_b64 vcc, exec, s[14:15]
	s_waitcnt lgkmcnt(0)
	s_barrier
	s_cbranch_vccnz .Lcold_3
.LBB0_744:
	v_cndmask_b32_e64 v83, v192, v191, s[48:49]
	v_cmp_neq_f32_e64 s[0:1], -v220, v83
	s_cmp_eq_u64 s[0:1], 0
	v_sub_f32_e32 v223, 0, v220
	s_cselect_b64 s[48:49], -1, 0
	v_mov_b32_e32 v216, 0
	s_cmp_lg_u64 s[48:49], 0
	s_cbranch_scc0 .Lcold_4
.Lnegc_keep_1:
	s_min_u32 s0, s16, 28
	s_add_i32 s6, s0, 3
	v_mad_u64_u32 v[34:35], s[0:1], v194, s6, v[206:207]
	global_load_dwordx4 v[162:165], v[34:35], off
	v_mad_u64_u32 v[34:35], s[0:1], v208, s6, v[210:211]
	s_lshl_b32 s40, s4, 18
	global_load_dwordx4 v[158:161], v[34:35], off
	v_lshl_add_u64 v[34:35], v[212:213], 0, s[40:41]
	s_mov_b32 s0, 0x80000
	v_add_co_u32_e32 v34, vcc, s0, v34
	v_max3_f32 v38, v240, v98, v99
	v_max3_f32 v39, v240, v100, v101
	s_nop 1
	v_addc_co_u32_e32 v35, vcc, 0, v35, vcc
	global_load_dwordx4 v[154:157], v[34:35], off offset:128
	ds_read_b128 v[34:37], v219
	ds_read_b128 v[174:177], v219 offset:32
	ds_read_b128 v[88:91], v219 offset:6656
	ds_read_b128 v[190:193], v219 offset:64
	ds_read_b128 v[178:181], v219 offset:6688
	ds_read_b128 v[186:189], v219 offset:6720
	v_max3_f32 v38, v38, v66, v67
	v_max3_f32 v39, v39, v68, v69
	s_waitcnt lgkmcnt(5)
	v_mfma_f32_32x32x16_bf16 v[50:65], v[34:37], v[130:133], v[114:129]
	ds_read_b128 v[182:185], v219 offset:96
	ds_read_b128 v[84:87], v219 offset:6752
	v_max3_f32 v38, v38, v102, v103
	v_max3_f32 v39, v39, v104, v105
	s_nop 0
	v_max3_f32 v38, v38, v70, v71
	v_max3_f32 v39, v39, v72, v73
	s_nop 0
	v_max3_f32 v34, v38, v106, v107
	v_max3_f32 v35, v39, v108, v109
	s_nop 0
	v_max3_f32 v96, v34, v74, v75
	v_max3_f32 v97, v35, v76, v77
	s_waitcnt lgkmcnt(5)
	v_mfma_f32_32x32x16_bf16 v[34:49], v[88:91], v[130:133], v[114:129]
	ds_read_b128 v[92:95], v219 offset:128
	ds_read_b128 v[88:91], v219 offset:6784
	ds_read_b64_tr_b16 v[170:171], v221 offset:34816
	ds_read_b64_tr_b16 v[172:173], v221 offset:35328
	ds_read_b64_tr_b16 v[166:167], v221 offset:38912
	ds_read_b64_tr_b16 v[168:169], v221 offset:39424
	v_mfma_f32_32x32x16_bf16 v[50:65], v[174:177], v[134:137], v[50:65]
	v_max3_f32 v96, v96, v110, v111
	v_max3_f32 v97, v97, v112, v113
	s_nop 0
	v_max3_f32 v96, v96, v78, v79
	v_max3_f32 v97, v97, v80, v81
	s_waitcnt lgkmcnt(9)
	v_mfma_f32_32x32x16_bf16 v[34:49], v[178:181], v[134:137], v[34:49]
	v_max_f32_e32 v96, v96, v97
	s_nop 0
	v_mov_b32_e32 v97, v96
	s_nop 1
	v_permlane32_swap_b32_e32 v96, v97
	v_max_f32_e32 v96, v96, v97
	s_nop 0
	v_cmp_lt_f32_e32 vcc, s2, v96
	v_cmp_gt_f32_e64 s[0:1], s3, v96
	s_or_b64 vcc, vcc, s[0:1]
	s_cmp_lg_u64 vcc, 0
	s_cselect_b64 s[14:15], -1, 0
	s_cbranch_vccnz .Lcold_5

.LBB0_747:
	ds_read_b128 v[224:227], v219 offset:160
	ds_read_b128 v[228:231], v219 offset:6816
	ds_read_b64_tr_b16 v[178:179], v221 offset:35840
	ds_read_b64_tr_b16 v[180:181], v221 offset:36352
	ds_read_b64_tr_b16 v[174:175], v221 offset:39936
	ds_read_b64_tr_b16 v[176:177], v221 offset:40448
	v_mfma_f32_32x32x16_bf16 v[50:65], v[190:193], v[138:141], v[50:65]
	v_exp_f32_e32 v96, v98
	v_exp_f32_e32 v97, v99
	v_exp_f32_e32 v98, v100
	v_exp_f32_e32 v99, v101
	s_waitcnt lgkmcnt(14)
	v_mfma_f32_32x32x16_bf16 v[34:49], v[186:189], v[138:141], v[34:49]
	v_exp_f32_e32 v100, v102
	v_exp_f32_e32 v102, v103
	v_exp_f32_e32 v103, v104
	v_exp_f32_e32 v186, v105
	s_waitcnt lgkmcnt(13)
	v_mfma_f32_32x32x16_bf16 v[50:65], v[182:185], v[142:145], v[50:65]
	v_exp_f32_e32 v101, v106
	v_exp_f32_e32 v104, v107
	v_exp_f32_e32 v105, v108
	v_exp_f32_e32 v106, v109
	s_waitcnt lgkmcnt(12)
	v_mfma_f32_32x32x16_bf16 v[34:49], v[84:87], v[142:145], v[34:49]
	v_exp_f32_e32 v84, v110
	v_exp_f32_e32 v85, v111
	v_exp_f32_e32 v86, v112
	v_exp_f32_e32 v87, v113
	s_waitcnt lgkmcnt(11)
	v_mfma_f32_32x32x16_bf16 v[50:65], v[92:95], v[146:149], v[50:65]
	s_waitcnt lgkmcnt(10)
	v_mfma_f32_32x32x16_bf16 v[34:49], v[88:91], v[146:149], v[34:49]
	s_waitcnt lgkmcnt(5)
	v_mfma_f32_32x32x16_bf16 v[50:65], v[224:227], v[150:153], v[50:65]
	s_waitcnt lgkmcnt(4)
	v_mfma_f32_32x32x16_bf16 v[34:49], v[228:231], v[150:153], v[34:49]
	v_cmp_eq_f32_e32 vcc, 1.0, v218
	s_cmp_lg_u64 vcc, exec
	s_cbranch_scc1 .Lcold_6

.Lcold_0:
	v_mov_b32_e32 v129, v192
	v_mov_b32_e32 v128, v192
	v_mov_b32_e32 v127, v192
	v_mov_b32_e32 v126, v192
	v_mov_b32_e32 v125, v192
	v_mov_b32_e32 v124, v192
	v_mov_b32_e32 v123, v192
	v_mov_b32_e32 v122, v192
	v_mov_b32_e32 v121, v192
	v_mov_b32_e32 v120, v192
	v_mov_b32_e32 v119, v192
	v_mov_b32_e32 v118, v192
	v_mov_b32_e32 v117, v192
	v_mov_b32_e32 v116, v192
	v_mov_b32_e32 v115, v192
	v_mov_b32_e32 v114, v192
	s_branch .Lnegc_keep_0
.Lcold_1:
	v_cmp_lt_f32_e32 vcc, 0, v0
	s_or_b64 vcc, vcc, s[0:1]
	s_nop 0
	v_cndmask_b32_e32 v190, 0, v0, vcc
	v_exp_f32_e64 v0, -v190
	v_pk_add_f32 v[50:51], v[50:51], v[190:191] op_sel_hi:[1,0] neg_lo:[0,1] neg_hi:[0,1]
	v_pk_add_f32 v[52:53], v[52:53], v[190:191] op_sel_hi:[1,0] neg_lo:[0,1] neg_hi:[0,1]
	v_pk_add_f32 v[54:55], v[54:55], v[190:191] op_sel_hi:[1,0] neg_lo:[0,1] neg_hi:[0,1]
	v_pk_add_f32 v[56:57], v[56:57], v[190:191] op_sel_hi:[1,0] neg_lo:[0,1] neg_hi:[0,1]
	v_pk_add_f32 v[58:59], v[58:59], v[190:191] op_sel_hi:[1,0] neg_lo:[0,1] neg_hi:[0,1]
	v_pk_add_f32 v[60:61], v[60:61], v[190:191] op_sel_hi:[1,0] neg_lo:[0,1] neg_hi:[0,1]
	v_pk_add_f32 v[62:63], v[62:63], v[190:191] op_sel_hi:[1,0] neg_lo:[0,1] neg_hi:[0,1]
	v_pk_add_f32 v[64:65], v[64:65], v[190:191] op_sel_hi:[1,0] neg_lo:[0,1] neg_hi:[0,1]
	v_sub_f32_e32 v49, v49, v190
	v_sub_f32_e32 v48, v48, v190
	v_sub_f32_e32 v47, v47, v190
	v_sub_f32_e32 v46, v46, v190
	v_sub_f32_e32 v45, v45, v190
	v_sub_f32_e32 v44, v44, v190
	v_sub_f32_e32 v43, v43, v190
	v_sub_f32_e32 v42, v42, v190
	v_sub_f32_e32 v41, v41, v190
	v_sub_f32_e32 v40, v40, v190
	v_sub_f32_e32 v39, v39, v190
	v_sub_f32_e32 v38, v38, v190
	v_sub_f32_e32 v37, v37, v190
	v_sub_f32_e32 v36, v36, v190
	v_sub_f32_e32 v35, v35, v190
	v_sub_f32_e32 v34, v34, v190
	v_add_f32_e32 v220, v220, v190
	s_branch .LBB0_736
.Lcold_2:
	v_pk_mul_f32 v[32:33], v[32:33], v[0:1] op_sel_hi:[1,0]
	v_pk_mul_f32 v[30:31], v[30:31], v[0:1] op_sel_hi:[1,0]
	v_pk_mul_f32 v[28:29], v[28:29], v[0:1] op_sel_hi:[1,0]
	v_pk_mul_f32 v[26:27], v[26:27], v[0:1] op_sel_hi:[1,0]
	v_pk_mul_f32 v[24:25], v[24:25], v[0:1] op_sel_hi:[1,0]
	v_pk_mul_f32 v[22:23], v[22:23], v[0:1] op_sel_hi:[1,0]
	v_pk_mul_f32 v[20:21], v[20:21], v[0:1] op_sel_hi:[1,0]
	v_pk_mul_f32 v[18:19], v[18:19], v[0:1] op_sel_hi:[1,0]
	v_pk_mul_f32 v[16:17], v[16:17], v[0:1] op_sel_hi:[1,0]
	v_pk_mul_f32 v[14:15], v[14:15], v[0:1] op_sel_hi:[1,0]
	v_pk_mul_f32 v[12:13], v[12:13], v[0:1] op_sel_hi:[1,0]
	v_pk_mul_f32 v[10:11], v[10:11], v[0:1] op_sel_hi:[1,0]
	v_pk_mul_f32 v[8:9], v[8:9], v[0:1] op_sel_hi:[1,0]
	v_pk_mul_f32 v[6:7], v[6:7], v[0:1] op_sel_hi:[1,0]
	v_pk_mul_f32 v[4:5], v[4:5], v[0:1] op_sel_hi:[1,0]
	v_pk_mul_f32 v[2:3], v[2:3], v[0:1] op_sel_hi:[1,0]
	s_branch .LBB0_738
.Lcold_3:
	v_sub_f32_e32 v113, v113, v190
	v_sub_f32_e32 v112, v112, v190
	v_sub_f32_e32 v111, v111, v190
	v_sub_f32_e32 v110, v110, v190
	v_sub_f32_e32 v109, v109, v190
	v_sub_f32_e32 v108, v108, v190
	v_sub_f32_e32 v107, v107, v190
	v_sub_f32_e32 v106, v106, v190
	v_sub_f32_e32 v105, v105, v190
	v_sub_f32_e32 v104, v104, v190
	v_sub_f32_e32 v103, v103, v190
	v_sub_f32_e32 v102, v102, v190
	v_sub_f32_e32 v101, v101, v190
	v_sub_f32_e32 v100, v100, v190
	v_sub_f32_e32 v99, v99, v190
	v_sub_f32_e32 v98, v98, v190
	v_sub_f32_e32 v81, v81, v190
	v_sub_f32_e32 v80, v80, v190
	v_sub_f32_e32 v79, v79, v190
	v_sub_f32_e32 v78, v78, v190
	v_sub_f32_e32 v77, v77, v190
	v_sub_f32_e32 v76, v76, v190
	v_sub_f32_e32 v75, v75, v190
	v_sub_f32_e32 v74, v74, v190
	v_sub_f32_e32 v73, v73, v190
	v_sub_f32_e32 v72, v72, v190
	v_sub_f32_e32 v71, v71, v190
	v_sub_f32_e32 v70, v70, v190
	v_sub_f32_e32 v69, v69, v190
	v_sub_f32_e32 v68, v68, v190
	v_sub_f32_e32 v67, v67, v190
	v_sub_f32_e32 v66, v66, v190
	s_branch .LBB0_744
.Lcold_4:
	v_mov_b32_e32 v129, v223
	v_mov_b32_e32 v128, v223
	v_mov_b32_e32 v127, v223
	v_mov_b32_e32 v126, v223
	v_mov_b32_e32 v125, v223
	v_mov_b32_e32 v124, v223
	v_mov_b32_e32 v123, v223
	v_mov_b32_e32 v122, v223
	v_mov_b32_e32 v121, v223
	v_mov_b32_e32 v120, v223
	v_mov_b32_e32 v119, v223
	v_mov_b32_e32 v118, v223
	v_mov_b32_e32 v117, v223
	v_mov_b32_e32 v116, v223
	v_mov_b32_e32 v115, v223
	v_mov_b32_e32 v114, v223
	s_branch .Lnegc_keep_1
.Lcold_5:
	v_cmp_lt_f32_e32 vcc, 0, v96
	s_or_b64 vcc, vcc, s[0:1]
	s_nop 0
	v_cndmask_b32_e32 v216, 0, v96, vcc
	v_exp_f32_e64 v218, -v216
	v_pk_add_f32 v[98:99], v[98:99], v[216:217] op_sel_hi:[1,0] neg_lo:[0,1] neg_hi:[0,1]
	v_pk_add_f32 v[100:101], v[100:101], v[216:217] op_sel_hi:[1,0] neg_lo:[0,1] neg_hi:[0,1]
	v_pk_add_f32 v[102:103], v[102:103], v[216:217] op_sel_hi:[1,0] neg_lo:[0,1] neg_hi:[0,1]
	v_pk_add_f32 v[104:105], v[104:105], v[216:217] op_sel_hi:[1,0] neg_lo:[0,1] neg_hi:[0,1]
	v_pk_add_f32 v[106:107], v[106:107], v[216:217] op_sel_hi:[1,0] neg_lo:[0,1] neg_hi:[0,1]
	v_pk_add_f32 v[108:109], v[108:109], v[216:217] op_sel_hi:[1,0] neg_lo:[0,1] neg_hi:[0,1]
	v_pk_add_f32 v[110:111], v[110:111], v[216:217] op_sel_hi:[1,0] neg_lo:[0,1] neg_hi:[0,1]
	v_pk_add_f32 v[112:113], v[112:113], v[216:217] op_sel_hi:[1,0] neg_lo:[0,1] neg_hi:[0,1]
	v_sub_f32_e32 v81, v81, v216
	v_sub_f32_e32 v80, v80, v216
	v_sub_f32_e32 v79, v79, v216
	v_sub_f32_e32 v78, v78, v216
	v_sub_f32_e32 v77, v77, v216
	v_sub_f32_e32 v76, v76, v216
	v_sub_f32_e32 v75, v75, v216
	v_sub_f32_e32 v74, v74, v216
	v_sub_f32_e32 v73, v73, v216
	v_sub_f32_e32 v72, v72, v216
	v_sub_f32_e32 v71, v71, v216
	v_sub_f32_e32 v70, v70, v216
	v_sub_f32_e32 v69, v69, v216
	v_sub_f32_e32 v68, v68, v216
	v_sub_f32_e32 v67, v67, v216
	v_sub_f32_e32 v66, v66, v216
	v_add_f32_e32 v220, v220, v216
	s_branch .LBB0_747
.Lcold_6:
	v_pk_mul_f32 v[32:33], v[32:33], v[218:219] op_sel_hi:[1,0]
	v_pk_mul_f32 v[30:31], v[30:31], v[218:219] op_sel_hi:[1,0]
	v_pk_mul_f32 v[28:29], v[28:29], v[218:219] op_sel_hi:[1,0]
	v_pk_mul_f32 v[26:27], v[26:27], v[218:219] op_sel_hi:[1,0]
	v_pk_mul_f32 v[24:25], v[24:25], v[218:219] op_sel_hi:[1,0]
	v_pk_mul_f32 v[22:23], v[22:23], v[218:219] op_sel_hi:[1,0]
	v_pk_mul_f32 v[20:21], v[20:21], v[218:219] op_sel_hi:[1,0]
	v_pk_mul_f32 v[18:19], v[18:19], v[218:219] op_sel_hi:[1,0]
	v_pk_mul_f32 v[16:17], v[16:17], v[218:219] op_sel_hi:[1,0]
	v_pk_mul_f32 v[14:15], v[14:15], v[218:219] op_sel_hi:[1,0]
	v_pk_mul_f32 v[12:13], v[12:13], v[218:219] op_sel_hi:[1,0]
	v_pk_mul_f32 v[10:11], v[10:11], v[218:219] op_sel_hi:[1,0]
	v_pk_mul_f32 v[8:9], v[8:9], v[218:219] op_sel_hi:[1,0]
	v_pk_mul_f32 v[6:7], v[6:7], v[218:219] op_sel_hi:[1,0]
	v_pk_mul_f32 v[4:5], v[4:5], v[218:219] op_sel_hi:[1,0]
	v_pk_mul_f32 v[2:3], v[2:3], v[218:219] op_sel_hi:[1,0]
	s_branch .LBB0_749

.Lcold_8:
	v_mov_b32_e32 v175, v218
	v_mov_b32_e32 v174, v218
	v_mov_b32_e32 v173, v218
	v_mov_b32_e32 v172, v218
	v_mov_b32_e32 v171, v218
	v_mov_b32_e32 v170, v218
	v_mov_b32_e32 v169, v218
	v_mov_b32_e32 v168, v218
	v_mov_b32_e32 v167, v218
	v_mov_b32_e32 v166, v218
	v_mov_b32_e32 v165, v218
	v_mov_b32_e32 v164, v218
	v_mov_b32_e32 v163, v218
	v_mov_b32_e32 v162, v218
	v_mov_b32_e32 v161, v218
	v_mov_b32_e32 v160, v218
	s_branch .Lnegc_keep_2
.Lcold_9:
	v_cmp_lt_f32_e32 vcc, 0, v0
	s_or_b64 vcc, vcc, s[0:1]
	s_nop 0
	v_cndmask_b32_e32 v0, 0, v0, vcc
	v_exp_f32_e64 v14, -v0
	v_pk_add_f32 v[128:129], v[128:129], v[0:1] op_sel_hi:[1,0] neg_lo:[0,1] neg_hi:[0,1]
	v_pk_add_f32 v[130:131], v[130:131], v[0:1] op_sel_hi:[1,0] neg_lo:[0,1] neg_hi:[0,1]
	v_pk_add_f32 v[132:133], v[132:133], v[0:1] op_sel_hi:[1,0] neg_lo:[0,1] neg_hi:[0,1]
	v_pk_add_f32 v[134:135], v[134:135], v[0:1] op_sel_hi:[1,0] neg_lo:[0,1] neg_hi:[0,1]
	v_pk_add_f32 v[136:137], v[136:137], v[0:1] op_sel_hi:[1,0] neg_lo:[0,1] neg_hi:[0,1]
	v_pk_add_f32 v[138:139], v[138:139], v[0:1] op_sel_hi:[1,0] neg_lo:[0,1] neg_hi:[0,1]
	v_pk_add_f32 v[140:141], v[140:141], v[0:1] op_sel_hi:[1,0] neg_lo:[0,1] neg_hi:[0,1]
	v_pk_add_f32 v[142:143], v[142:143], v[0:1] op_sel_hi:[1,0] neg_lo:[0,1] neg_hi:[0,1]
	v_sub_f32_e32 v95, v95, v0
	v_sub_f32_e32 v94, v94, v0
	v_sub_f32_e32 v93, v93, v0
	v_sub_f32_e32 v92, v92, v0
	v_sub_f32_e32 v91, v91, v0
	v_sub_f32_e32 v90, v90, v0
	v_sub_f32_e32 v89, v89, v0
	v_sub_f32_e32 v88, v88, v0
	v_sub_f32_e32 v87, v87, v0
	v_sub_f32_e32 v86, v86, v0
	v_sub_f32_e32 v85, v85, v0
	v_sub_f32_e32 v84, v84, v0
	v_sub_f32_e32 v83, v83, v0
	v_sub_f32_e32 v82, v82, v0
	v_sub_f32_e32 v81, v81, v0
	v_sub_f32_e32 v80, v80, v0
	v_add_f32_e32 v217, v217, v0
	s_branch .LBB0_932
.Lcold_10:
	v_pk_mul_f32 v[78:79], v[14:15], v[78:79] op_sel_hi:[0,1]
	v_pk_mul_f32 v[76:77], v[14:15], v[76:77] op_sel_hi:[0,1]
	v_pk_mul_f32 v[74:75], v[14:15], v[74:75] op_sel_hi:[0,1]
	v_pk_mul_f32 v[72:73], v[14:15], v[72:73] op_sel_hi:[0,1]
	v_pk_mul_f32 v[70:71], v[14:15], v[70:71] op_sel_hi:[0,1]
	v_pk_mul_f32 v[68:69], v[14:15], v[68:69] op_sel_hi:[0,1]
	v_pk_mul_f32 v[66:67], v[14:15], v[66:67] op_sel_hi:[0,1]
	v_pk_mul_f32 v[64:65], v[14:15], v[64:65] op_sel_hi:[0,1]
	v_pk_mul_f32 v[62:63], v[14:15], v[62:63] op_sel_hi:[0,1]
	v_pk_mul_f32 v[60:61], v[14:15], v[60:61] op_sel_hi:[0,1]
	v_pk_mul_f32 v[58:59], v[14:15], v[58:59] op_sel_hi:[0,1]
	v_pk_mul_f32 v[56:57], v[14:15], v[56:57] op_sel_hi:[0,1]
	v_pk_mul_f32 v[54:55], v[14:15], v[54:55] op_sel_hi:[0,1]
	v_pk_mul_f32 v[52:53], v[14:15], v[52:53] op_sel_hi:[0,1]
	v_pk_mul_f32 v[50:51], v[14:15], v[50:51] op_sel_hi:[0,1]
	v_pk_mul_f32 v[48:49], v[14:15], v[48:49] op_sel_hi:[0,1]
	v_pk_mul_f32 v[46:47], v[14:15], v[46:47] op_sel_hi:[0,1]
	v_pk_mul_f32 v[44:45], v[14:15], v[44:45] op_sel_hi:[0,1]
	v_pk_mul_f32 v[42:43], v[14:15], v[42:43] op_sel_hi:[0,1]
	v_pk_mul_f32 v[40:41], v[14:15], v[40:41] op_sel_hi:[0,1]
	v_pk_mul_f32 v[38:39], v[14:15], v[38:39] op_sel_hi:[0,1]
	v_pk_mul_f32 v[36:37], v[14:15], v[36:37] op_sel_hi:[0,1]
	v_pk_mul_f32 v[34:35], v[14:15], v[34:35] op_sel_hi:[0,1]
	v_pk_mul_f32 v[32:33], v[14:15], v[32:33] op_sel_hi:[0,1]
	v_pk_mul_f32 v[30:31], v[14:15], v[30:31] op_sel_hi:[0,1]
	v_pk_mul_f32 v[28:29], v[14:15], v[28:29] op_sel_hi:[0,1]
	v_pk_mul_f32 v[26:27], v[14:15], v[26:27] op_sel_hi:[0,1]
	v_pk_mul_f32 v[24:25], v[14:15], v[24:25] op_sel_hi:[0,1]
	v_pk_mul_f32 v[22:23], v[14:15], v[22:23] op_sel_hi:[0,1]
	v_pk_mul_f32 v[20:21], v[14:15], v[20:21] op_sel_hi:[0,1]
	v_pk_mul_f32 v[18:19], v[14:15], v[18:19] op_sel_hi:[0,1]
	v_pk_mul_f32 v[16:17], v[14:15], v[16:17] op_sel_hi:[0,1]
	s_branch .LBB0_934

.Lcold_12:
	v_cmp_lt_f32_e32 vcc, 0, v0
	s_or_b64 vcc, vcc, s[0:1]
	s_nop 0
	v_cndmask_b32_e32 v0, 0, v0, vcc
	v_exp_f32_e64 v112, -v0
	v_pk_add_f32 v[144:145], v[144:145], v[0:1] op_sel_hi:[1,0] neg_lo:[0,1] neg_hi:[0,1]
	v_pk_add_f32 v[146:147], v[146:147], v[0:1] op_sel_hi:[1,0] neg_lo:[0,1] neg_hi:[0,1]
	v_pk_add_f32 v[148:149], v[148:149], v[0:1] op_sel_hi:[1,0] neg_lo:[0,1] neg_hi:[0,1]
	v_pk_add_f32 v[150:151], v[150:151], v[0:1] op_sel_hi:[1,0] neg_lo:[0,1] neg_hi:[0,1]
	v_pk_add_f32 v[152:153], v[152:153], v[0:1] op_sel_hi:[1,0] neg_lo:[0,1] neg_hi:[0,1]
	v_pk_add_f32 v[154:155], v[154:155], v[0:1] op_sel_hi:[1,0] neg_lo:[0,1] neg_hi:[0,1]
	v_pk_add_f32 v[156:157], v[156:157], v[0:1] op_sel_hi:[1,0] neg_lo:[0,1] neg_hi:[0,1]
	v_pk_add_f32 v[158:159], v[158:159], v[0:1] op_sel_hi:[1,0] neg_lo:[0,1] neg_hi:[0,1]
	v_sub_f32_e32 v111, v111, v0
	v_sub_f32_e32 v110, v110, v0
	v_sub_f32_e32 v109, v109, v0
	v_sub_f32_e32 v108, v108, v0
	v_sub_f32_e32 v107, v107, v0
	v_sub_f32_e32 v106, v106, v0
	v_sub_f32_e32 v105, v105, v0
	v_sub_f32_e32 v104, v104, v0
	v_sub_f32_e32 v103, v103, v0
	v_sub_f32_e32 v102, v102, v0
	v_sub_f32_e32 v101, v101, v0
	v_sub_f32_e32 v100, v100, v0
	v_sub_f32_e32 v99, v99, v0
	v_sub_f32_e32 v98, v98, v0
	v_sub_f32_e32 v97, v97, v0
	v_sub_f32_e32 v96, v96, v0
	v_add_f32_e32 v217, v217, v0
	s_branch .LBB0_949
.Lcold_13:
	v_pk_mul_f32 v[78:79], v[112:113], v[78:79] op_sel_hi:[0,1]
	v_pk_mul_f32 v[76:77], v[112:113], v[76:77] op_sel_hi:[0,1]
	v_pk_mul_f32 v[74:75], v[112:113], v[74:75] op_sel_hi:[0,1]
	v_pk_mul_f32 v[72:73], v[112:113], v[72:73] op_sel_hi:[0,1]
	v_pk_mul_f32 v[70:71], v[112:113], v[70:71] op_sel_hi:[0,1]
	v_pk_mul_f32 v[68:69], v[112:113], v[68:69] op_sel_hi:[0,1]
	v_pk_mul_f32 v[66:67], v[112:113], v[66:67] op_sel_hi:[0,1]
	v_pk_mul_f32 v[64:65], v[112:113], v[64:65] op_sel_hi:[0,1]
	v_pk_mul_f32 v[62:63], v[112:113], v[62:63] op_sel_hi:[0,1]
	v_pk_mul_f32 v[60:61], v[112:113], v[60:61] op_sel_hi:[0,1]
	v_pk_mul_f32 v[58:59], v[112:113], v[58:59] op_sel_hi:[0,1]
	v_pk_mul_f32 v[56:57], v[112:113], v[56:57] op_sel_hi:[0,1]
	v_pk_mul_f32 v[54:55], v[112:113], v[54:55] op_sel_hi:[0,1]
	v_pk_mul_f32 v[52:53], v[112:113], v[52:53] op_sel_hi:[0,1]
	v_pk_mul_f32 v[50:51], v[112:113], v[50:51] op_sel_hi:[0,1]
	v_pk_mul_f32 v[48:49], v[112:113], v[48:49] op_sel_hi:[0,1]
	v_pk_mul_f32 v[46:47], v[112:113], v[46:47] op_sel_hi:[0,1]
	v_pk_mul_f32 v[44:45], v[112:113], v[44:45] op_sel_hi:[0,1]
	v_pk_mul_f32 v[42:43], v[112:113], v[42:43] op_sel_hi:[0,1]
	v_pk_mul_f32 v[40:41], v[112:113], v[40:41] op_sel_hi:[0,1]
	v_pk_mul_f32 v[38:39], v[112:113], v[38:39] op_sel_hi:[0,1]
	v_pk_mul_f32 v[36:37], v[112:113], v[36:37] op_sel_hi:[0,1]
	v_pk_mul_f32 v[34:35], v[112:113], v[34:35] op_sel_hi:[0,1]
	v_pk_mul_f32 v[32:33], v[112:113], v[32:33] op_sel_hi:[0,1]
	v_pk_mul_f32 v[30:31], v[112:113], v[30:31] op_sel_hi:[0,1]
	v_pk_mul_f32 v[28:29], v[112:113], v[28:29] op_sel_hi:[0,1]
	v_pk_mul_f32 v[26:27], v[112:113], v[26:27] op_sel_hi:[0,1]
	v_pk_mul_f32 v[24:25], v[112:113], v[24:25] op_sel_hi:[0,1]
	v_pk_mul_f32 v[22:23], v[112:113], v[22:23] op_sel_hi:[0,1]
	v_pk_mul_f32 v[20:21], v[112:113], v[20:21] op_sel_hi:[0,1]
	v_pk_mul_f32 v[18:19], v[112:113], v[18:19] op_sel_hi:[0,1]
	v_pk_mul_f32 v[16:17], v[112:113], v[16:17] op_sel_hi:[0,1]
	s_branch .LBB0_951

.LBB0_833:
	s_nop 0
	v_cmp_neq_f32_e32 vcc, s5, v128
	s_nop 1
	v_cndmask_b32_e32 v141, 0, v128, vcc
	v_sub_f32_e32 v0, v127, v141
	v_exp_f32_e32 v0, v0
	v_add_u32_e32 v36, 0x12400, v126
	v_add_u32_e32 v37, 0x12600, v126
	v_add_u32_e32 v38, 0x13400, v126
	v_add_u32_e32 v39, 0x13600, v126
	v_mfma_f32_32x32x16_bf16 v[66:81], v[60:63], v[106:109], v[66:81]
	ds_read_b64_tr_b16 v[40:41], v36
	ds_read_b64_tr_b16 v[42:43], v37
	ds_read_b64_tr_b16 v[36:37], v38
	ds_read_b64_tr_b16 v[38:39], v39
	v_sub_f32_e32 v127, v142, v141
	v_sub_f32_e32 v142, v143, v141
	v_sub_f32_e32 v143, v144, v141
	v_sub_f32_e32 v144, v146, v141
	v_exp_f32_e32 v127, v127
	v_exp_f32_e32 v142, v142
	v_exp_f32_e32 v143, v143
	v_exp_f32_e32 v144, v144
	s_waitcnt lgkmcnt(10)
	v_mfma_f32_32x32x16_bf16 v[82:97], v[56:59], v[106:109], v[82:97]
	v_sub_f32_e32 v56, v145, v141
	v_sub_f32_e32 v57, v147, v141
	v_sub_f32_e32 v58, v148, v141
	v_sub_f32_e32 v59, v150, v141
	v_exp_f32_e32 v56, v56
	v_exp_f32_e32 v57, v57
	v_exp_f32_e32 v58, v58
	v_exp_f32_e32 v59, v59
	s_waitcnt lgkmcnt(9)
	v_mfma_f32_32x32x16_bf16 v[66:81], v[52:55], v[110:113], v[66:81]
	v_sub_f32_e32 v52, v149, v141
	v_sub_f32_e32 v53, v151, v141
	v_sub_f32_e32 v54, v152, v141
	v_sub_f32_e32 v55, v153, v141
	v_exp_f32_e32 v52, v52
	v_exp_f32_e32 v53, v53
	v_exp_f32_e32 v54, v54
	v_exp_f32_e32 v55, v55
	s_waitcnt lgkmcnt(8)
	v_mfma_f32_32x32x16_bf16 v[82:97], v[48:51], v[110:113], v[82:97]
	v_sub_f32_e32 v48, v64, v141
	v_sub_f32_e32 v49, v65, v141
	v_sub_f32_e32 v50, v154, v141
	v_sub_f32_e32 v51, v155, v141
	v_exp_f32_e32 v48, v48
	v_exp_f32_e32 v49, v49
	v_exp_f32_e32 v50, v50
	v_exp_f32_e32 v51, v51
	v_cmp_eq_f32_e32 vcc, 1.0, v0
	s_cmp_lg_u64 vcc, exec
	s_cbranch_scc1 .Lcold_7

.LBB0_929:
	s_waitcnt lgkmcnt(0)
	v_sub_f32_e32 v218, v0, v217
	s_add_i32 s34, s4, 2
	v_cmp_neq_f32_e32 vcc, v218, v112
	s_cmp_eq_u64 vcc, 0
	s_cselect_b64 s[46:47], -1, 0
	s_cmp_lg_u64 s[46:47], 0
	s_cbranch_scc0 .Lcold_8
.Lnegc_keep_2:
	s_min_u32 s0, s34, 29
	s_add_i32 s0, s0, 2
	v_mul_u32_u24_e32 v0, s0, v206
	v_add_co_u32_e32 v10, vcc, s93, v212
	v_lshl_add_u64 v[2:3], v[208:209], 0, v[0:1]
	s_nop 0
	v_addc_co_u32_e32 v11, vcc, 0, v213, vcc
	global_load_dwordx4 v[2:5], v[2:3], off
	s_nop 0
	global_load_dwordx4 v[6:9], v[212:213], off
	s_nop 0
	global_load_dwordx4 v[10:13], v[10:11], off
	ds_read_b128 v[96:99], v215 offset:9216
	ds_read_b128 v[220:223], v215 offset:9248
	ds_read_b128 v[114:117], v215 offset:13824
	ds_read_b128 v[224:227], v215 offset:13856
	v_max3_f32 v0, v240, v128, v129
	v_max3_f32 v14, v240, v130, v131
	s_nop 0
	v_max3_f32 v0, v0, v80, v81
	v_max3_f32 v14, v14, v82, v83
	s_waitcnt lgkmcnt(3)
	v_mfma_f32_32x32x16_bf16 v[144:159], v[96:99], v[176:179], v[160:175]
	ds_read_b128 v[192:195], v215 offset:9280
	ds_read_b128 v[118:121], v215 offset:13888
	v_max3_f32 v0, v0, v132, v133
	v_max3_f32 v14, v14, v134, v135
	s_nop 0
	v_max3_f32 v0, v0, v84, v85
	v_max3_f32 v14, v14, v86, v87
	s_waitcnt lgkmcnt(3)
	v_mfma_f32_32x32x16_bf16 v[96:111], v[114:117], v[176:179], v[160:175]
	v_max3_f32 v0, v0, v136, v137
	v_max3_f32 v14, v14, v138, v139
	s_nop 0
	v_max3_f32 v0, v0, v88, v89
	v_max3_f32 v14, v14, v90, v91
	v_mfma_f32_32x32x16_bf16 v[144:159], v[220:223], v[180:183], v[144:159]
	ds_read_b128 v[122:125], v215 offset:9312
	ds_read_b128 v[114:117], v215 offset:13920
	v_max3_f32 v0, v0, v140, v141
	v_max3_f32 v14, v14, v142, v143
	s_nop 0
	v_max3_f32 v0, v0, v92, v93
	v_max3_f32 v14, v14, v94, v95
	s_waitcnt lgkmcnt(4)
	v_mfma_f32_32x32x16_bf16 v[96:111], v[224:227], v[180:183], v[96:111]
	v_max_f32_e32 v0, v0, v14
	s_nop 0
	v_mov_b32_e32 v14, v0
	s_nop 1
	v_permlane32_swap_b32_e32 v0, v14
	v_max_f32_e32 v0, v0, v14
	s_nop 0
	v_cmp_lt_f32_e32 vcc, s2, v0
	v_cmp_gt_f32_e64 s[0:1], s3, v0
	s_or_b64 vcc, vcc, s[0:1]
	s_cmp_lg_u64 vcc, 0
	s_cselect_b64 s[20:21], -1, 0
	s_cbranch_vccnz .Lcold_9

.LBB0_932:
	s_waitcnt lgkmcnt(3)
	v_mfma_f32_32x32x16_bf16 v[144:159], v[192:195], v[184:187], v[144:159]
	v_exp_f32_e32 v126, v128
	v_exp_f32_e32 v127, v129
	v_exp_f32_e32 v128, v130
	v_exp_f32_e32 v129, v131
	s_waitcnt lgkmcnt(2)
	v_mfma_f32_32x32x16_bf16 v[96:111], v[118:121], v[184:187], v[96:111]
	v_exp_f32_e32 v130, v132
	v_exp_f32_e32 v131, v133
	v_exp_f32_e32 v132, v134
	v_exp_f32_e32 v133, v135
	s_waitcnt lgkmcnt(1)
	v_mfma_f32_32x32x16_bf16 v[144:159], v[122:125], v[188:191], v[144:159]
	v_exp_f32_e32 v118, v136
	v_exp_f32_e32 v119, v137
	v_exp_f32_e32 v120, v138
	v_exp_f32_e32 v121, v139
	s_waitcnt lgkmcnt(0)
	v_mfma_f32_32x32x16_bf16 v[96:111], v[114:117], v[188:191], v[96:111]
	v_exp_f32_e32 v114, v140
	v_exp_f32_e32 v115, v141
	v_exp_f32_e32 v116, v142
	v_exp_f32_e32 v117, v143
	v_cmp_eq_f32_e32 vcc, 1.0, v14
	s_cmp_lg_u64 vcc, exec
	s_cbranch_scc1 .Lcold_10

.LBB0_946:
	v_cndmask_b32_e64 v115, v218, v112, s[46:47]
	s_waitcnt lgkmcnt(0)
	v_sub_f32_e32 v218, v0, v217
	s_add_i32 s0, s4, 4
	v_cmp_neq_f32_e32 vcc, v218, v115
	s_cmp_eq_u64 vcc, 0
	s_cselect_b64 s[46:47], -1, 0
	s_cmp_lg_u64 s[46:47], 0
	s_cbranch_scc0 .Lcold_11
.Lnegc_keep_3:
	s_min_u32 s0, s0, 31
	s_min_u32 s1, s34, 28
	s_mul_i32 s40, s0, 0x108000
	s_add_i32 s1, s1, 3
	v_lshl_add_u64 v[6:7], v[210:211], 0, s[40:41]
	v_mul_u32_u24_e32 v0, s1, v206
	v_add_co_u32_e32 v10, vcc, s93, v6
	v_lshl_add_u64 v[2:3], v[208:209], 0, v[0:1]
	s_nop 0
	v_addc_co_u32_e32 v11, vcc, 0, v7, vcc
	global_load_dwordx4 v[2:5], v[2:3], off
	s_nop 0
	global_load_dwordx4 v[6:9], v[6:7], off
	s_nop 0
	global_load_dwordx4 v[10:13], v[10:11], off
	ds_read_b128 v[80:83], v215
	ds_read_b128 v[196:199], v215 offset:32
	ds_read_b128 v[116:119], v215 offset:4608
	ds_read_b128 v[200:203], v215 offset:4640
	v_max3_f32 v0, v240, v144, v145
	v_max3_f32 v84, v240, v146, v147
	s_nop 0
	v_max3_f32 v0, v0, v96, v97
	v_max3_f32 v84, v84, v98, v99
	s_waitcnt lgkmcnt(3)
	v_mfma_f32_32x32x16_bf16 v[128:143], v[80:83], v[176:179], v[160:175]
	ds_read_b128 v[192:195], v215 offset:64
	ds_read_b128 v[120:123], v215 offset:4672
	v_max3_f32 v0, v0, v148, v149
	v_max3_f32 v84, v84, v150, v151
	s_nop 0
	v_max3_f32 v0, v0, v100, v101
	v_max3_f32 v84, v84, v102, v103
	s_nop 0
	v_max3_f32 v80, v84, v154, v155
	v_max3_f32 v0, v0, v152, v153
	s_nop 0
	v_max3_f32 v112, v80, v106, v107
	s_waitcnt lgkmcnt(3)
	v_mfma_f32_32x32x16_bf16 v[80:95], v[116:119], v[176:179], v[160:175]
	v_max3_f32 v0, v0, v104, v105
	v_mfma_f32_32x32x16_bf16 v[128:143], v[196:199], v[180:183], v[128:143]
	ds_read_b128 v[124:127], v215 offset:96
	ds_read_b128 v[116:119], v215 offset:4704
	v_max3_f32 v0, v0, v156, v157
	v_max3_f32 v112, v112, v158, v159
	s_nop 0
	v_max3_f32 v0, v0, v108, v109
	v_max3_f32 v112, v112, v110, v111
	s_waitcnt lgkmcnt(4)
	v_mfma_f32_32x32x16_bf16 v[80:95], v[200:203], v[180:183], v[80:95]
	v_max_f32_e32 v0, v0, v112
	s_nop 0
	v_mov_b32_e32 v112, v0
	s_nop 1
	v_permlane32_swap_b32_e32 v0, v112
	v_max_f32_e32 v0, v0, v112
	s_nop 0
	v_cmp_lt_f32_e32 vcc, s2, v0
	v_cmp_gt_f32_e64 s[0:1], s3, v0
	s_or_b64 vcc, vcc, s[0:1]
	s_cmp_lg_u64 vcc, 0
	s_cselect_b64 s[20:21], -1, 0
	s_cbranch_vccnz .Lcold_12

.LBB0_949:
	s_waitcnt lgkmcnt(3)
	v_mfma_f32_32x32x16_bf16 v[128:143], v[192:195], v[184:187], v[128:143]
	v_exp_f32_e32 v144, v144
	v_exp_f32_e32 v145, v145
	v_exp_f32_e32 v146, v146
	v_exp_f32_e32 v147, v147
	s_waitcnt lgkmcnt(2)
	v_mfma_f32_32x32x16_bf16 v[80:95], v[120:123], v[184:187], v[80:95]
	v_exp_f32_e32 v148, v148
	v_exp_f32_e32 v149, v149
	v_exp_f32_e32 v150, v150
	v_exp_f32_e32 v151, v151
	s_waitcnt lgkmcnt(1)
	v_mfma_f32_32x32x16_bf16 v[128:143], v[124:127], v[188:191], v[128:143]
	v_exp_f32_e32 v120, v152
	v_exp_f32_e32 v121, v153
	v_exp_f32_e32 v122, v154
	v_exp_f32_e32 v123, v155
	s_waitcnt lgkmcnt(0)
	v_mfma_f32_32x32x16_bf16 v[80:95], v[116:119], v[188:191], v[80:95]
	v_exp_f32_e32 v116, v156
	v_exp_f32_e32 v117, v157
	v_exp_f32_e32 v118, v158
	v_exp_f32_e32 v119, v159
	v_cmp_eq_f32_e32 vcc, 1.0, v112
	s_cmp_lg_u64 vcc, exec
	s_cbranch_scc1 .Lcold_13

.LBB0_975:
	s_waitcnt lgkmcnt(0)
	v_sub_f32_e32 v218, v0, v217
	s_add_i32 s17, s4, 2
	v_cmp_neq_f32_e32 vcc, v218, v112
	s_cmp_eq_u64 vcc, 0
	s_cselect_b64 s[46:47], -1, 0
	s_cmp_lg_u64 s[46:47], 0
	s_cbranch_scc0 .Lcold_14
.Lnegc_keep_4:
	s_min_u32 s0, s17, 29
	s_add_i32 s0, s0, 2
	v_mul_u32_u24_e32 v0, s0, v206
	v_add_co_u32_e32 v10, vcc, s93, v212
	v_lshl_add_u64 v[2:3], v[208:209], 0, v[0:1]
	s_nop 0
	v_addc_co_u32_e32 v11, vcc, 0, v213, vcc
	global_load_dwordx4 v[2:5], v[2:3], off
	s_nop 0
	global_load_dwordx4 v[6:9], v[212:213], off
	s_nop 0
	global_load_dwordx4 v[10:13], v[10:11], off
	ds_read_b128 v[96:99], v215 offset:9216
	ds_read_b128 v[196:199], v215 offset:9248
	ds_read_b128 v[114:117], v215 offset:13824
	ds_read_b128 v[200:203], v215 offset:13856
	v_max3_f32 v0, v240, v128, v129
	v_max3_f32 v14, v240, v130, v131
	s_nop 0
	v_max3_f32 v0, v0, v80, v81
	v_max3_f32 v14, v14, v82, v83
	s_waitcnt lgkmcnt(3)
	v_mfma_f32_32x32x16_bf16 v[144:159], v[96:99], v[184:187], v[160:175]
	ds_read_b128 v[192:195], v215 offset:9280
	ds_read_b128 v[118:121], v215 offset:13888
	v_max3_f32 v0, v0, v132, v133
	v_max3_f32 v14, v14, v134, v135
	s_nop 0
	v_max3_f32 v0, v0, v84, v85
	v_max3_f32 v14, v14, v86, v87
	s_waitcnt lgkmcnt(3)
	v_mfma_f32_32x32x16_bf16 v[96:111], v[114:117], v[184:187], v[160:175]
	v_max3_f32 v0, v0, v136, v137
	v_max3_f32 v14, v14, v138, v139
	s_nop 0
	v_max3_f32 v0, v0, v88, v89
	v_max3_f32 v14, v14, v90, v91
	v_mfma_f32_32x32x16_bf16 v[144:159], v[196:199], v[176:179], v[144:159]
	ds_read_b128 v[122:125], v215 offset:9312
	ds_read_b128 v[114:117], v215 offset:13920
	v_max3_f32 v0, v0, v140, v141
	v_max3_f32 v14, v14, v142, v143
	s_nop 0
	v_max3_f32 v0, v0, v92, v93
	v_max3_f32 v14, v14, v94, v95
	s_waitcnt lgkmcnt(4)
	v_mfma_f32_32x32x16_bf16 v[96:111], v[200:203], v[176:179], v[96:111]
	v_max_f32_e32 v0, v0, v14
	s_nop 0
	v_mov_b32_e32 v14, v0
	s_nop 1
	v_permlane32_swap_b32_e32 v0, v14
	v_max_f32_e32 v0, v0, v14
	s_nop 0
	v_cmp_lt_f32_e32 vcc, s2, v0
	v_cmp_gt_f32_e64 s[0:1], s3, v0
	s_or_b64 vcc, vcc, s[0:1]
	s_cmp_lg_u64 vcc, 0
	s_cselect_b64 s[14:15], -1, 0
	s_cbranch_vccnz .Lcold_15

.LBB0_978:
	s_waitcnt lgkmcnt(3)
	v_mfma_f32_32x32x16_bf16 v[144:159], v[192:195], v[180:183], v[144:159]
	v_exp_f32_e32 v126, v128
	v_exp_f32_e32 v127, v129
	v_exp_f32_e32 v128, v130
	v_exp_f32_e32 v129, v131
	s_waitcnt lgkmcnt(2)
	v_mfma_f32_32x32x16_bf16 v[96:111], v[118:121], v[180:183], v[96:111]
	v_exp_f32_e32 v130, v132
	v_exp_f32_e32 v131, v133
	v_exp_f32_e32 v132, v134
	v_exp_f32_e32 v133, v135
	s_waitcnt lgkmcnt(1)
	v_mfma_f32_32x32x16_bf16 v[144:159], v[122:125], v[188:191], v[144:159]
	v_exp_f32_e32 v118, v136
	v_exp_f32_e32 v119, v137
	v_exp_f32_e32 v120, v138
	v_exp_f32_e32 v121, v139
	s_waitcnt lgkmcnt(0)
	v_mfma_f32_32x32x16_bf16 v[96:111], v[114:117], v[188:191], v[96:111]
	v_exp_f32_e32 v114, v140
	v_exp_f32_e32 v115, v141
	v_exp_f32_e32 v116, v142
	v_exp_f32_e32 v117, v143
	v_cmp_eq_f32_e32 vcc, 1.0, v14
	s_cmp_lg_u64 vcc, exec
	s_cbranch_scc1 .Lcold_16

.Lnegc_keep_5:
	s_min_u32 s1, s17, 28
	s_add_i32 s1, s1, 3
	v_mul_u32_u24_e32 v0, s1, v206
	s_min_u32 s0, s0, 31
	v_lshl_add_u64 v[2:3], v[208:209], 0, v[0:1]
	s_mul_i32 s40, s0, 0x108000
	global_load_dwordx4 v[10:13], v[2:3], off
	v_lshl_add_u64 v[2:3], v[210:211], 0, s[40:41]
	v_add_co_u32_e32 v6, vcc, s93, v2
	v_max3_f32 v0, v240, v144, v145
	v_max3_f32 v84, v240, v146, v147
	s_nop 1
	v_addc_co_u32_e32 v7, vcc, 0, v3, vcc
	global_load_dwordx4 v[2:5], v[2:3], off
	s_nop 0
	global_load_dwordx4 v[6:9], v[6:7], off
	ds_read_b128 v[80:83], v215
	ds_read_b128 v[196:199], v215 offset:32
	ds_read_b128 v[116:119], v215 offset:4608
	ds_read_b128 v[200:203], v215 offset:4640
	v_max3_f32 v0, v0, v96, v97
	v_max3_f32 v84, v84, v98, v99
	s_waitcnt lgkmcnt(3)
	v_mfma_f32_32x32x16_bf16 v[128:143], v[80:83], v[184:187], v[160:175]
	ds_read_b128 v[192:195], v215 offset:64
	ds_read_b128 v[120:123], v215 offset:4672
	v_max3_f32 v0, v0, v148, v149
	v_max3_f32 v84, v84, v150, v151
	s_nop 0
	v_max3_f32 v0, v0, v100, v101
	v_max3_f32 v84, v84, v102, v103
	s_nop 0
	v_max3_f32 v80, v84, v154, v155
	v_max3_f32 v0, v0, v152, v153
	s_nop 0
	v_max3_f32 v112, v80, v106, v107
	s_waitcnt lgkmcnt(3)
	v_mfma_f32_32x32x16_bf16 v[80:95], v[116:119], v[184:187], v[160:175]
	v_max3_f32 v0, v0, v104, v105
	v_mfma_f32_32x32x16_bf16 v[128:143], v[196:199], v[176:179], v[128:143]
	ds_read_b128 v[124:127], v215 offset:96
	ds_read_b128 v[116:119], v215 offset:4704
	v_max3_f32 v0, v0, v156, v157
	v_max3_f32 v112, v112, v158, v159
	s_nop 0
	v_max3_f32 v0, v0, v108, v109
	v_max3_f32 v112, v112, v110, v111
	s_waitcnt lgkmcnt(4)
	v_mfma_f32_32x32x16_bf16 v[80:95], v[200:203], v[176:179], v[80:95]
	v_max_f32_e32 v0, v0, v112
	s_nop 0
	v_mov_b32_e32 v112, v0
	s_nop 1
	v_permlane32_swap_b32_e32 v0, v112
	v_max_f32_e32 v0, v0, v112
	s_nop 0
	v_cmp_lt_f32_e32 vcc, s2, v0
	v_cmp_gt_f32_e64 s[0:1], s3, v0
	s_or_b64 vcc, vcc, s[0:1]
	s_cmp_lg_u64 vcc, 0
	s_cselect_b64 s[14:15], -1, 0
	s_cbranch_vccnz .Lcold_18

.LBB0_995:
	s_waitcnt lgkmcnt(3)
	v_mfma_f32_32x32x16_bf16 v[128:143], v[192:195], v[180:183], v[128:143]
	v_exp_f32_e32 v144, v144
	v_exp_f32_e32 v145, v145
	v_exp_f32_e32 v146, v146
	v_exp_f32_e32 v147, v147
	s_waitcnt lgkmcnt(2)
	v_mfma_f32_32x32x16_bf16 v[80:95], v[120:123], v[180:183], v[80:95]
	v_exp_f32_e32 v148, v148
	v_exp_f32_e32 v149, v149
	v_exp_f32_e32 v150, v150
	v_exp_f32_e32 v151, v151
	s_waitcnt lgkmcnt(1)
	v_mfma_f32_32x32x16_bf16 v[128:143], v[124:127], v[188:191], v[128:143]
	v_exp_f32_e32 v120, v152
	v_exp_f32_e32 v121, v153
	v_exp_f32_e32 v122, v154
	v_exp_f32_e32 v123, v155
	s_waitcnt lgkmcnt(0)
	v_mfma_f32_32x32x16_bf16 v[80:95], v[116:119], v[188:191], v[80:95]
	v_exp_f32_e32 v116, v156
	v_exp_f32_e32 v117, v157
	v_exp_f32_e32 v118, v158
	v_exp_f32_e32 v119, v159
	v_cmp_eq_f32_e32 vcc, 1.0, v112
	s_cmp_lg_u64 vcc, exec
	s_cbranch_scc1 .Lcold_19
